# speedup vs baseline: 1.0091x; 1.0005x over previous
;   __device__ __forceinline__ const float* in(int i) const { return reinterpret_cast<const float*>(ld64(i * 8)); }
;   __device__ __forceinline__ unsigned char* ws() const { return reinterpret_cast<unsigned char*>(ld64(27 * 8)); }
; __device__ __forceinline__ void phase_convert(const PRef& p) {
;   unsigned char* ws = p.ws();
;   constexpr int U0 = 704, U1 = U0 + 352, U2 = U1 + 704, U3 = U2 + 352, U4 = U3 + 384, U5 = U4 + 128;
;   for (int u = blockIdx.x; u < U5; u += gridDim.x) {
;     if (u < U0)      convert_weight(p.in(7), p.in(8), true, 1024, DFF, 5632, (bf16*)(ws + WS_W1A), u);
;     else if (u < U1) convert_weight(p.in(9), nullptr, false, DFF, 1024, 1024, (bf16*)(ws + WS_WD1), u - U0);
;     else if (u < U2) convert_weight(p.in(21), p.in(22), true, 1024, DFF, 5632, (bf16*)(ws + WS_W1B), u - U1);
;     else if (u < U3) convert_weight(p.in(23), nullptr, false, DFF, 1024, 1024, (bf16*)(ws + WS_WD2), u - U2);
;     else if (u < U4) convert_weight(p.in(12), nullptr, false, 1024, 3072, 3072, (bf16*)(ws + WS_WIN), u - U3);
;     else             convert_weight(p.in(18), nullptr, false, 1024, 1024, 1024, (bf16*)(ws + WS_WOUT), u - U4);
;   }
.LBB0_1138:
	v_readlane_b32 s0, v254, 10
	s_cmp_lg_u32 s0, 1
	s_cbranch_scc1 .Lmy_cv_return
	v_readlane_b32 s0, v254, 0
	s_cmpk_lt_u32 s0, 150
	s_cbranch_scc1 .Lmy_cv_return
	s_sub_i32 s18, s0, 150
	s_addk_i32 s18, 1056
	s_lshl_b32 s17, s18, 8
	s_or_b32 s17, s17, 15
	s_lshl_b32 s16, s18, 3
	s_add_i32 s16, s16, 0x7be00
	s_movk_i32 s100, 106
	s_movk_i32 s101, 1760
	v_mov_b32_e32 v2, 0x23fd8
	ds_read_b64 v[2:3], v2
	s_waitcnt lgkmcnt(0)
	v_readfirstlane_b32 s4, v2
	v_readfirstlane_b32 s5, v3
	s_branch .Lmy_cv_entry

;   __device__ __forceinline__ const float* in(int i) const { return reinterpret_cast<const float*>(ld64(i * 8)); }
;   __device__ __forceinline__ unsigned char* ws() const { return reinterpret_cast<unsigned char*>(ld64(27 * 8)); }
; __device__ __forceinline__ void phase_convert(const PRef& p) {
;   unsigned char* ws = p.ws();
;   constexpr int U0 = 704, U1 = U0 + 352, U2 = U1 + 704, U3 = U2 + 352, U4 = U3 + 384, U5 = U4 + 128;
;   for (int u = blockIdx.x; u < U5; u += gridDim.x) {
;     if (u < U0)      convert_weight(p.in(7), p.in(8), true, 1024, DFF, 5632, (bf16*)(ws + WS_W1A), u);
;     else if (u < U1) convert_weight(p.in(9), nullptr, false, DFF, 1024, 1024, (bf16*)(ws + WS_WD1), u - U0);
;     else if (u < U2) convert_weight(p.in(21), p.in(22), true, 1024, DFF, 5632, (bf16*)(ws + WS_W1B), u - U1);
;     else if (u < U3) convert_weight(p.in(23), nullptr, false, DFF, 1024, 1024, (bf16*)(ws + WS_WD2), u - U2);
;     else if (u < U4) convert_weight(p.in(12), nullptr, false, 1024, 3072, 3072, (bf16*)(ws + WS_WIN), u - U3);
;     else             convert_weight(p.in(18), nullptr, false, 1024, 1024, 1024, (bf16*)(ws + WS_WOUT), u - U4);
;   }
.LBB0_1143:
	s_or_b64 exec, exec, s[0:1]
	s_movk_i32 s101, 0xa40
	s_mov_b64 s[0:1], src_shared_base
	v_readlane_b32 s0, v254, 5
	s_cmp_lg_u32 s0, -1
	s_cselect_b32 s0, s0, 0
	v_mov_b32_e32 v2, s0
	v_readlane_b32 s0, v254, 6
	s_cselect_b32 s4, s1, 0
	s_cmp_lg_u32 s0, -1
	v_mov_b32_e32 v3, s4
	s_cselect_b32 s0, s0, 0
	s_cselect_b32 s1, s1, 0
	flat_load_dword v0, v[2:3] sc0 sc1
	s_waitcnt vmcnt(0)
	v_mov_b32_e32 v2, s0
	v_mov_b32_e32 v3, s1
	flat_load_dword v2, v[2:3] sc0 sc1
	s_waitcnt vmcnt(0)
	v_readlane_b32 s0, v254, 19
	v_readlane_b32 s1, v254, 20
	s_andn2_b64 vcc, exec, s[0:1]
	s_waitcnt lgkmcnt(0)
	v_readfirstlane_b32 s4, v0
	v_readfirstlane_b32 s5, v2
	s_cbranch_vccnz .LBB0_1166
	v_readlane_b32 s100, v254, 1
	v_readlane_b32 s16, v254, 43
	v_readlane_b32 s17, v254, 41
	v_readlane_b32 s18, v254, 0
.Lmy_cv_entry:
	s_add_u32 s6, s4, 0x2700000
	s_addc_u32 s7, s5, 0
	s_add_u32 s8, s4, 0x2100000
	s_addc_u32 s9, s5, 0
	s_add_u32 s10, s4, 0x1b80000
	s_addc_u32 s11, s5, 0
	s_add_u32 s12, s4, 0x1080000
	s_addc_u32 s13, s5, 0
	s_add_u32 s14, s4, 0xb00000
	s_addc_u32 s15, s5, 0
	s_branch .LBB0_1146
.LBB0_1145:
	s_add_i32 s18, s18, s100
	s_lshl_b32 s0, s100, 8
	s_add_i32 s17, s17, s0
	s_lshl_b32 s0, s100, 3
	s_add_i32 s16, s16, s0
	s_cmp_lt_i32 s18, s101
	v_readlane_b32 s1, v254, 2
	flat_store_dwordx4 v[6:7], v[2:5] offset:16
	s_cbranch_scc0 .LBB0_1166
.LBB0_1146:
	s_cmpk_lg_i32 s101, 0xa40
	s_cbranch_scc1 .Lmy_cv_noskip
	s_cmpk_lt_i32 s18, 1056
	s_cbranch_scc1 .Lmy_cv_noskip
	s_cmpk_ge_i32 s18, 1760
	s_cbranch_scc1 .Lmy_cv_noskip
	s_add_i32 s18, s18, s100
	s_lshl_b32 s0, s100, 8
	s_add_i32 s17, s17, s0
	s_lshl_b32 s0, s100, 3
	s_add_i32 s16, s16, s0
	s_cmp_lt_i32 s18, s101
	s_cbranch_scc1 .LBB0_1146
	s_branch .LBB0_1166

;   __device__ __forceinline__ const float* in(int i) const { return reinterpret_cast<const float*>(ld64(i * 8)); }
;   __device__ __forceinline__ float* out() const { return reinterpret_cast<float*>(ld64(26 * 8)); }
;   __device__ __forceinline__ unsigned char* ws() const { return reinterpret_cast<unsigned char*>(ld64(27 * 8)); }
; __device__ __forceinline__ int opaque_tid() { int t = threadIdx.x; asm volatile("" : "+v"(t)); return t; }
; template <int MODE>
; __device__ __forceinline__ void phase_rows(const PRef& p, const float* __restrict__ vsrc, const float* __restrict__ g1, const float* __restrict__ g2, float coef, int nsplit) {
;   const int tidx = opaque_tid();
;   const int lane = tidx & 63, wave = tidx >> 6;
;   bf16* xn = (bf16*)(p.ws() + WS_XN);
;   float* hbuf = p.out() + O_Y;
;   const float* xp = p.in(0); const float* xs_ = p.in(1);
;   for (int row = blockIdx.x * 8 + wave; row < MT; row += gridDim.x * 8) {
;     float4 h[4];
;     if (MODE == 0) {
;       const float4* xs = reinterpret_cast<const float4*>(row < MP ? xp + (size_t)row * DM : xs_ + (size_t)(row - MP) * DM);
; #pragma unroll
;       for (int i = 0; i < 4; ++i) { const f32x4v t = __builtin_nontemporal_load(reinterpret_cast<const f32x4v*>(xs) + lane + 64 * i); h[i] = make_float4(t[0], t[1], t[2], t[3]); }
.LBB0_1166:
	s_cmpk_lg_i32 s101, 0xa40
	s_cbranch_scc1 .Lmy_cv_return
	s_add_i32 s0, 0, 0x23f30
	s_cmp_lg_u32 s0, -1
	s_cselect_b32 s0, s0, 0
	s_mov_b64 s[4:5], src_shared_base
	s_cselect_b32 s1, s5, 0
	v_mov_b32_e32 v2, s0
	s_add_i32 s0, 0, 0x23f34
	s_cmp_lg_u32 s0, -1
	v_mov_b32_e32 v3, s1
	s_cselect_b32 s0, s0, 0
	s_cselect_b32 s1, s5, 0
	flat_load_dword v0, v[2:3] sc0 sc1
	s_waitcnt vmcnt(0)
	v_mov_b32_e32 v2, s0
	v_mov_b32_e32 v3, s1
	flat_load_dword v2, v[2:3] sc0 sc1
	s_waitcnt vmcnt(0)
	v_readlane_b32 s0, v254, 5
	s_cmp_lg_u32 s0, -1
	s_cselect_b32 s0, s0, 0
	s_cselect_b32 s1, s5, 0
	v_mov_b32_e32 v3, s1
	s_waitcnt lgkmcnt(0)
	v_readfirstlane_b32 s8, v0
	v_mov_b32_e32 v0, v171
	v_readfirstlane_b32 s9, v2
	v_mov_b32_e32 v2, s0
	v_readlane_b32 s0, v254, 6
	s_cmp_lg_u32 s0, -1
	s_cselect_b32 s0, s0, 0
	s_cselect_b32 s1, s5, 0
	flat_load_dword v5, v[2:3] sc0 sc1
	s_waitcnt vmcnt(0)
	v_mov_b32_e32 v2, s0
	v_mov_b32_e32 v3, s1
	flat_load_dword v2, v[2:3] sc0 sc1
	s_waitcnt vmcnt(0)
	s_add_i32 s0, 0, 0x23fd0
	s_cmp_lg_u32 s0, -1
	s_cselect_b32 s0, s0, 0
	s_cselect_b32 s1, s5, 0
	v_mov_b32_e32 v3, s1
	v_ashrrev_i32_e32 v4, 6, v0
	s_waitcnt lgkmcnt(0)
	v_readfirstlane_b32 s10, v5
	v_readfirstlane_b32 s11, v2
	v_mov_b32_e32 v2, s0
	s_add_i32 s0, 0, 0x23fd4
	s_cmp_lg_u32 s0, -1
	flat_load_dword v2, v[2:3] sc0 sc1
	s_waitcnt vmcnt(0)
	s_cselect_b32 s0, s0, 0
	s_cselect_b32 s1, s5, 0
	s_waitcnt lgkmcnt(0)
	v_mov_b32_e32 v2, s0
	s_add_i32 s0, 0, 0x23f00
	v_mov_b32_e32 v3, s1
	s_cmp_lg_u32 s0, -1
	flat_load_dword v2, v[2:3] sc0 sc1
	s_waitcnt vmcnt(0)
	s_cselect_b32 s0, s0, 0
	s_cselect_b32 s1, s5, 0
	s_waitcnt lgkmcnt(0)
	v_mov_b32_e32 v2, s0
	s_add_i32 s0, 0, 0x23f04
	s_cmp_lg_u32 s0, -1
	v_mov_b32_e32 v3, s1
	s_cselect_b32 s0, s0, 0
	s_cselect_b32 s1, s5, 0
	flat_load_dword v5, v[2:3] sc0 sc1
	s_waitcnt vmcnt(0)
	v_mov_b32_e32 v2, s0
	v_mov_b32_e32 v3, s1
	flat_load_dword v2, v[2:3] sc0 sc1
	s_waitcnt vmcnt(0)
	s_add_i32 s4, 0, 0x23f08
	s_cmp_lg_u32 s4, -1
	s_cselect_b32 s4, s4, 0
	s_cselect_b32 s6, s5, 0
	v_mov_b32_e32 v3, s6
	v_readlane_b32 s6, v254, 42
	s_waitcnt lgkmcnt(0)
	v_readfirstlane_b32 s0, v5
	v_add_u32_e32 v10, s6, v4
	s_movk_i32 s6, 0x4100
	v_readfirstlane_b32 s1, v2
	v_mov_b32_e32 v2, s4
	s_add_i32 s4, 0, 0x23f0c
	s_cmp_lg_u32 s4, -1
	s_cselect_b32 s4, s4, 0
	s_cselect_b32 s5, s5, 0
	flat_load_dword v5, v[2:3] sc0 sc1
	s_waitcnt vmcnt(0)
	v_mov_b32_e32 v2, s4
	v_mov_b32_e32 v3, s5
	flat_load_dword v2, v[2:3] sc0 sc1
	s_waitcnt vmcnt(0)
	v_cmp_gt_i32_e32 vcc, s6, v10
	s_waitcnt lgkmcnt(0)
	v_readfirstlane_b32 s4, v5
	v_readfirstlane_b32 s5, v2
	s_and_saveexec_b64 s[6:7], vcc
	s_cbranch_execz .LBB0_1173
	v_and_b32_e32 v6, 63, v0
	v_lshlrev_b32_e32 v0, 4, v6
	v_lshl_add_u64 v[12:13], s[8:9], 0, v[0:1]
	flat_load_dwordx4 v[2:5], v[12:13]
	flat_load_dwordx4 v[228:231], v[12:13] offset:1024
	flat_load_dwordx4 v[232:235], v[12:13] offset:2048
	flat_load_dwordx4 v[236:239], v[12:13] offset:3072
	v_xor_b32_e32 v0, 32, v193
	v_cmp_lt_i32_e32 vcc, v0, v195
	s_mov_b64 s[8:9], 0x2a00000
	s_nop 0
	v_cndmask_b32_e32 v0, v193, v0, vcc
	v_cmp_lt_i32_e32 vcc, v253, v195
	v_lshlrev_b32_e32 v16, 2, v0
	s_nop 0
	v_cndmask_b32_e32 v0, v193, v253, vcc
	v_cmp_lt_i32_e32 vcc, v210, v195
	v_lshlrev_b32_e32 v17, 2, v0
	s_nop 0
	v_cndmask_b32_e32 v0, v193, v210, vcc
	v_lshlrev_b32_e32 v18, 2, v0
	v_xor_b32_e32 v0, 4, v193
	v_cmp_lt_i32_e32 vcc, v0, v195
	s_nop 1
	v_cndmask_b32_e32 v0, v193, v0, vcc
	v_lshlrev_b32_e32 v19, 2, v0
	v_xor_b32_e32 v0, 2, v193
	v_cmp_lt_i32_e32 vcc, v0, v195
	s_nop 1
	v_cndmask_b32_e32 v0, v193, v0, vcc
	v_lshlrev_b32_e32 v20, 2, v0
	v_xor_b32_e32 v0, 1, v193
	v_cmp_lt_i32_e32 vcc, v0, v195
	s_nop 1
	v_cndmask_b32_e32 v0, v193, v0, vcc
	v_lshlrev_b32_e32 v21, 2, v0
	v_lshlrev_b32_e32 v0, 3, v6
	v_lshl_add_u64 v[8:9], s[10:11], 0, v[0:1]
	v_lshl_add_u64 v[14:15], v[8:9], 0, s[8:9]
	s_mov_b64 s[8:9], 0
	v_lshlrev_b32_e32 v0, 4, v6
	s_branch .LBB0_1169
